# scan: skip the two intra-chunk attention fragments that are identically zero under the causal mask (2 LDS reads + 2 MFMAs per compute wave per chunk; the scan loop is LDS-bandwidth-bound)
# baseline (speedup 1.0000x reference)
.LBB0_1548:
	ds_read_b128 v[52:55], v51 offset:0
	ds_read_b128 v[56:59], v51 offset:16384
	ds_read_b128 v[60:63], v51 offset:4096
	ds_read_b128 v[64:67], v51 offset:20480
	ds_read_b128 v[68:71], v51 offset:8192
	ds_read_b128 v[72:75], v51 offset:24576
	ds_read_b128 v[76:79], v51 offset:12288
	ds_read_b128 v[80:83], v51 offset:28672
	ds_read_b128 v[116:119], v50 offset:57344
	ds_read_b128 v[208:211], v50 offset:57360
	ds_read_b32 v212, v214
	ds_read_b128 v[84:87], v51 offset:1024
	ds_read_b128 v[88:91], v51 offset:17408
	ds_read_b128 v[92:95], v51 offset:5120
	ds_read_b128 v[96:99], v51 offset:21504
	v_mfma_f32_16x16x32_bf16 v[16:19], v[160:163], v[216:219], v[16:19]
	v_mfma_f32_16x16x32_bf16 v[16:19], v[164:167], v[220:223], v[16:19]
	v_cvt_pk_bf16_f32 v40, v8, v9
	v_mfma_f32_16x16x32_bf16 v[20:23], v[172:175], v[216:219], v[20:23]
	v_mfma_f32_16x16x32_bf16 v[20:23], v[248:251], v[220:223], v[20:23]
	v_cvt_pk_bf16_f32 v41, v10, v11
	v_mfma_f32_16x16x32_bf16 v[24:27], v[232:235], v[216:219], v[24:27]
	v_mfma_f32_16x16x32_bf16 v[24:27], v[236:239], v[220:223], v[24:27]
	v_cvt_pk_bf16_f32 v42, v12, v13
	v_mfma_f32_16x16x32_bf16 v[28:31], v[240:243], v[216:219], v[28:31]
	v_mfma_f32_16x16x32_bf16 v[28:31], v[244:247], v[220:223], v[28:31]
	v_cvt_pk_bf16_f32 v43, v14, v15
	s_waitcnt lgkmcnt(14)
	v_mfma_f32_16x16x32_bf16 v[176:179], v[52:55], v[44:47], 0
	ds_read_b128 v[100:103], v51 offset:9216
	s_waitcnt lgkmcnt(14)
	v_mfma_f32_16x16x32_bf16 v[192:195], v[56:59], v[44:47], 0
	ds_read_b128 v[104:107], v51 offset:25600
	s_waitcnt lgkmcnt(14)
	v_mfma_f32_16x16x32_bf16 v[180:183], v[60:63], v[44:47], 0
	ds_read_b128 v[108:111], v51 offset:13312
	v_cvt_pk_bf16_f32 v36, v16, v17
	v_cvt_pk_bf16_f32 v37, v18, v19
	s_waitcnt lgkmcnt(14)
	v_mfma_f32_16x16x32_bf16 v[196:199], v[64:67], v[44:47], 0
	ds_read_b128 v[112:115], v51 offset:29696
	v_cvt_pk_bf16_f32 v38, v20, v21
	v_cvt_pk_bf16_f32 v39, v22, v23
	s_waitcnt lgkmcnt(14)
	v_mfma_f32_16x16x32_bf16 v[184:187], v[68:71], v[44:47], 0
	v_cvt_pk_bf16_f32 v32, v24, v25
	v_cvt_pk_bf16_f32 v33, v26, v27
	s_waitcnt lgkmcnt(13)
	v_mfma_f32_16x16x32_bf16 v[200:203], v[72:75], v[44:47], 0
	v_cvt_pk_bf16_f32 v34, v28, v29
	v_cvt_pk_bf16_f32 v35, v30, v31
	s_waitcnt lgkmcnt(12)
	v_mfma_f32_16x16x32_bf16 v[188:191], v[76:79], v[44:47], 0
	s_waitcnt lgkmcnt(10)
	v_lshlrev_b32_e32 v232, 16, v116
	v_and_b32_e32 v233, 0xffff0000, v116
	v_mfma_f32_16x16x32_bf16 v[204:207], v[80:83], v[44:47], 0
	v_lshlrev_b32_e32 v234, 16, v117
	v_and_b32_e32 v235, 0xffff0000, v117
	ds_read_b128 v[128:131], v51 offset:2048
	ds_read_b128 v[132:135], v51 offset:18432
	ds_read_b128 v[136:139], v51 offset:6144
	ds_read_b128 v[140:143], v51 offset:22528
	s_waitcnt lgkmcnt(11)
	v_mfma_f32_16x16x32_bf16 v[176:179], v[84:87], v[40:43], v[176:179]
	ds_read_b128 v[144:147], v51 offset:10240
	v_lshlrev_b32_e32 v236, 16, v118
	v_and_b32_e32 v237, 0xffff0000, v118
	s_waitcnt lgkmcnt(11)
	v_mfma_f32_16x16x32_bf16 v[192:195], v[88:91], v[40:43], v[192:195]
	ds_read_b128 v[148:151], v51 offset:26624
	v_lshlrev_b32_e32 v238, 16, v119
	v_and_b32_e32 v239, 0xffff0000, v119
	s_waitcnt lgkmcnt(11)
	v_mfma_f32_16x16x32_bf16 v[180:183], v[92:95], v[40:43], v[180:183]
	ds_read_b128 v[152:155], v51 offset:14336
	v_lshlrev_b32_e32 v240, 16, v208
	v_and_b32_e32 v241, 0xffff0000, v208
	s_waitcnt lgkmcnt(11)
	v_mfma_f32_16x16x32_bf16 v[196:199], v[96:99], v[40:43], v[196:199]
	ds_read_b128 v[156:159], v51 offset:30720
	v_lshlrev_b32_e32 v242, 16, v209
	v_and_b32_e32 v243, 0xffff0000, v209
	s_waitcnt lgkmcnt(11)
	v_mfma_f32_16x16x32_bf16 v[184:187], v[100:103], v[40:43], v[184:187]
	v_lshlrev_b32_e32 v244, 16, v210
	v_and_b32_e32 v245, 0xffff0000, v210
	s_waitcnt lgkmcnt(10)
	v_mfma_f32_16x16x32_bf16 v[200:203], v[104:107], v[40:43], v[200:203]
	v_lshlrev_b32_e32 v246, 16, v211
	v_and_b32_e32 v247, 0xffff0000, v211
	s_waitcnt lgkmcnt(9)
	v_mfma_f32_16x16x32_bf16 v[188:191], v[108:111], v[40:43], v[188:191]
	v_mul_f32_e32 v0, v212, v0
	v_mul_f32_e32 v1, v212, v1
	s_waitcnt lgkmcnt(8)
	v_mfma_f32_16x16x32_bf16 v[204:207], v[112:115], v[40:43], v[204:207]
	v_mul_f32_e32 v2, v212, v2
	v_mul_f32_e32 v3, v212, v3
	ds_read_b128 v[52:55], v51 offset:3072
	ds_read_b128 v[56:59], v51 offset:7168
	ds_read_b128 v[60:63], v51 offset:11264
	ds_read_b128 v[64:67], v51 offset:15360
	s_waitcnt lgkmcnt(11)
	v_mfma_f32_16x16x32_bf16 v[176:179], v[128:131], v[36:39], v[176:179]
	ds_read_b128 v[68:71], v51 offset:19456
	v_mul_f32_e32 v4, v212, v4
	v_mul_f32_e32 v5, v212, v5
	s_waitcnt lgkmcnt(11)
	v_mfma_f32_16x16x32_bf16 v[192:195], v[132:135], v[36:39], v[192:195]
	ds_read_b128 v[72:75], v51 offset:23552
	v_mul_f32_e32 v6, v212, v6
	v_mul_f32_e32 v7, v212, v7
	s_waitcnt lgkmcnt(11)
	v_mfma_f32_16x16x32_bf16 v[180:183], v[136:139], v[36:39], v[180:183]
	ds_read_b128 v[76:79], v51 offset:27648
	v_mul_f32_e32 v8, v212, v8
	v_mul_f32_e32 v9, v212, v9
	s_waitcnt lgkmcnt(11)
	v_mfma_f32_16x16x32_bf16 v[196:199], v[140:143], v[36:39], v[196:199]
	ds_read_b128 v[80:83], v51 offset:31744
	v_mul_f32_e32 v10, v212, v10
	v_mul_f32_e32 v11, v212, v11
	s_waitcnt lgkmcnt(11)
	v_mfma_f32_16x16x32_bf16 v[184:187], v[144:147], v[36:39], v[184:187]
	v_mul_f32_e32 v12, v212, v12
	v_mul_f32_e32 v13, v212, v13
	s_waitcnt lgkmcnt(10)
	v_mfma_f32_16x16x32_bf16 v[200:203], v[148:151], v[36:39], v[200:203]
	v_mul_f32_e32 v14, v212, v14
	v_mul_f32_e32 v15, v212, v15
	s_waitcnt lgkmcnt(9)
	v_mfma_f32_16x16x32_bf16 v[188:191], v[152:155], v[36:39], v[188:191]
	v_mul_f32_e32 v16, v212, v16
	v_mul_f32_e32 v17, v212, v17
	s_waitcnt lgkmcnt(8)
	v_mfma_f32_16x16x32_bf16 v[204:207], v[156:159], v[36:39], v[204:207]
	v_mul_f32_e32 v18, v212, v18
	v_mul_f32_e32 v19, v212, v19
	ds_read_b128 v[84:87], v51 offset:49152
	ds_read_b128 v[88:91], v51 offset:51200
	ds_read_b128 v[92:95], v51 offset:53248
	ds_read_b128 v[96:99], v51 offset:55296
	s_waitcnt lgkmcnt(11)
	v_mfma_f32_16x16x32_bf16 v[176:179], v[52:55], v[32:35], v[176:179]
	v_mul_f32_e32 v20, v212, v20
	v_mul_f32_e32 v21, v212, v21
	v_mul_f32_e32 v22, v212, v22
	s_waitcnt lgkmcnt(10)
	v_mfma_f32_16x16x32_bf16 v[180:183], v[56:59], v[32:35], v[180:183]
	v_mul_f32_e32 v23, v212, v23
	v_mul_f32_e32 v24, v212, v24
	v_mul_f32_e32 v25, v212, v25
	s_waitcnt lgkmcnt(9)
	v_mfma_f32_16x16x32_bf16 v[184:187], v[60:63], v[32:35], v[184:187]
	ds_read_b128 v[108:111], v51 offset:54272
	v_mul_f32_e32 v26, v212, v26
	v_mul_f32_e32 v27, v212, v27
	v_mul_f32_e32 v28, v212, v28
	s_waitcnt lgkmcnt(9)
	v_mfma_f32_16x16x32_bf16 v[188:191], v[64:67], v[32:35], v[188:191]
	ds_read_b128 v[112:115], v51 offset:56320
	v_mul_f32_e32 v29, v212, v29
	v_mul_f32_e32 v30, v212, v30
	v_mul_f32_e32 v31, v212, v31
	s_waitcnt lgkmcnt(9)
	v_mfma_f32_16x16x32_bf16 v[192:195], v[68:71], v[32:35], v[192:195]
	v_sub_f32_e32 v232, v232, v176
	v_sub_f32_e32 v233, v233, v177
	v_sub_f32_e32 v234, v234, v178
	v_sub_f32_e32 v235, v235, v179
	s_waitcnt lgkmcnt(8)
	v_mfma_f32_16x16x32_bf16 v[196:199], v[72:75], v[32:35], v[196:199]
	v_sub_f32_e32 v236, v236, v180
	v_sub_f32_e32 v237, v237, v181
	v_sub_f32_e32 v238, v238, v182
	v_sub_f32_e32 v239, v239, v183
	s_waitcnt lgkmcnt(7)
	v_mfma_f32_16x16x32_bf16 v[200:203], v[76:79], v[32:35], v[200:203]
	v_cvt_pk_bf16_f32 v216, v232, v233
	v_cvt_pk_bf16_f32 v217, v234, v235
	v_cvt_pk_bf16_f32 v218, v236, v237
	v_cvt_pk_bf16_f32 v219, v238, v239
	s_waitcnt lgkmcnt(6)
	v_mfma_f32_16x16x32_bf16 v[204:207], v[80:83], v[32:35], v[204:207]
	v_sub_f32_e32 v240, v240, v184
	v_sub_f32_e32 v241, v241, v185
	v_sub_f32_e32 v242, v242, v186
	v_sub_f32_e32 v243, v243, v187
	v_sub_f32_e32 v244, v244, v188
	v_sub_f32_e32 v245, v245, v189
	v_sub_f32_e32 v246, v246, v190
	v_sub_f32_e32 v247, v247, v191
	ds_read_b128 v[128:131], v51 offset:32768
	ds_read_b128 v[132:135], v51 offset:33792
	ds_read_b128 v[136:139], v51 offset:34816
	ds_read_b128 v[140:143], v51 offset:35840
	ds_read_b128 v[144:147], v51 offset:36864
	ds_read_b128 v[148:151], v51 offset:37888
	s_waitcnt lgkmcnt(11)
	v_mfma_f32_16x16x32_bf16 v[192:195], v[84:87], v[216:219], v[192:195]
	v_cvt_pk_bf16_f32 v220, v240, v241
	v_cvt_pk_bf16_f32 v221, v242, v243
	s_waitcnt lgkmcnt(10)
	v_mfma_f32_16x16x32_bf16 v[196:199], v[88:91], v[216:219], v[196:199]
	v_cvt_pk_bf16_f32 v222, v244, v245
	v_cvt_pk_bf16_f32 v223, v246, v247
	s_waitcnt lgkmcnt(9)
	v_mfma_f32_16x16x32_bf16 v[200:203], v[92:95], v[216:219], v[200:203]
	ds_read_b128 v[152:155], v51 offset:38912
	s_waitcnt lgkmcnt(9)
	v_mfma_f32_16x16x32_bf16 v[204:207], v[96:99], v[216:219], v[204:207]
	ds_read_b128 v[156:159], v51 offset:39936
	s_waitcnt lgkmcnt(9)
	v_mfma_f32_16x16x32_bf16 v[200:203], v[108:111], v[220:223], v[200:203]
	s_waitcnt lgkmcnt(8)
	v_mfma_f32_16x16x32_bf16 v[204:207], v[112:115], v[220:223], v[204:207]
	ds_read_b128 v[160:163], v51 offset:40960
	ds_read_b128 v[164:167], v51 offset:41984
	ds_read_b128 v[172:175], v51 offset:43008
	ds_read_b128 v[248:251], v51 offset:44032
	ds_read_b128 v[232:235], v51 offset:45056
	ds_read_b128 v[236:239], v51 offset:46080
	ds_read_b128 v[240:243], v51 offset:47104
	s_add_i32 s0, s0, 1
	s_and_b32 s1, s0, 1
	s_lshl_b32 s8, s1, 16
	s_lshl_b32 s1, s1, 2
	s_add_i32 s9, s8, s79
	s_add_i32 s1, s1, 0x20000
	s_waitcnt lgkmcnt(14)
	v_mfma_f32_16x16x32_bf16 v[0:3], v[128:131], v[216:219], v[0:3]
	ds_read_b128 v[244:247], v51 offset:48128
	s_waitcnt lgkmcnt(14)
	v_mfma_f32_16x16x32_bf16 v[0:3], v[132:135], v[220:223], v[0:3]
	v_add_u32_e32 v50, s9, v124
	v_mov_b32_e32 v214, s1
	s_waitcnt lgkmcnt(13)
	v_mfma_f32_16x16x32_bf16 v[4:7], v[136:139], v[216:219], v[4:7]
	s_waitcnt lgkmcnt(12)
	v_mfma_f32_16x16x32_bf16 v[4:7], v[140:143], v[220:223], v[4:7]
	v_cvt_pk_bf16_f32 v224, v192, v193
	v_cvt_pk_bf16_f32 v225, v194, v195
	v_cvt_pk_bf16_f32 v226, v196, v197
	v_cvt_pk_bf16_f32 v227, v198, v199
	s_waitcnt lgkmcnt(11)
	v_mfma_f32_16x16x32_bf16 v[8:11], v[144:147], v[216:219], v[8:11]
	s_waitcnt lgkmcnt(10)
	v_mfma_f32_16x16x32_bf16 v[8:11], v[148:151], v[220:223], v[8:11]
	v_cvt_pk_bf16_f32 v228, v200, v201
	v_cvt_pk_bf16_f32 v229, v202, v203
	v_cvt_pk_bf16_f32 v230, v204, v205
	v_cvt_pk_bf16_f32 v231, v206, v207
	global_store_dwordx4 v[48:49], v[224:227], off
	s_waitcnt lgkmcnt(9)
	v_mfma_f32_16x16x32_bf16 v[12:15], v[152:155], v[216:219], v[12:15]
	v_cvt_pk_bf16_f32 v44, v0, v1
	v_cvt_pk_bf16_f32 v45, v2, v3
	v_cvt_pk_bf16_f32 v46, v4, v5
	v_cvt_pk_bf16_f32 v47, v6, v7
	global_store_dwordx4 v[48:49], v[228:231], off offset:16
	v_add_u32_e32 v51, s8, v120
	s_mov_b64 s[8:9], 0x68000
	v_lshl_add_u64 v[48:49], v[48:49], 0, s[8:9]
	s_cmpk_lg_i32 s0, 0x100
	s_waitcnt lgkmcnt(0)
	v_mfma_f32_16x16x32_bf16 v[12:15], v[156:159], v[220:223], v[12:15]
	s_barrier
	s_cbranch_scc1 .LBB0_1548
	s_mov_b64 s[0:1], 0
